# attention K and V tiles both staged by LDS-DMA; V^T natural key order at 144B row stride read with ds_read_b128; P halves exchanged with v_permlane32_swap
# baseline (speedup 1.0000x reference)
; DI void attn_phase(ldsp lds, const bf16_t* Q, const bf16_t* KN, const bf16_t* KR, const bf16_t* VT, bf16_t* O, int vcu, int G) {
;     ...
;     const int tid = tid_, wid = __builtin_amdgcn_readfirstlane(tid >> 6), lane = tid & 63, l31 = lane & 31, hh = lane >> 5;
;     for (int pr = vcu; pr < 1024; pr += G) {
;         const int bh = pr >> 4, jj = pr & 15, b = bh >> 3, h = bh & 7;
;         const size_t tok0 = (size_t)b * SEQ;
; #pragma unroll 1
;         for (int half = 0; half < 2; ++half) {
;             const int qb = half == 0 ? 31 - jj : jj;
;             const int q0 = qb * 256 + wid * 32;
;             bf16x8 qf[12];
;             { const bf16_t* qp = Q + (tok0 + q0 + l31) * 1536 + h * 192 + hh * 8;
; #pragma unroll
;               for (int ks = 0; ks < 12; ++ks) qf[ks] = *(const bf16x8*)(qp + ks * 16); }
;             f32x16 o[4];
; #pragma unroll
;             for (int d = 0; d < 4; ++d)
; #pragma unroll
;                 for (int r = 0; r < 16; ++r) o[d][r] = 0.f;
;             float mrun = -1e30f, lrun = 0.f;
;             const int ntiles = (qb + 1) * 4;
;             u32x4 kreg[3], vreg[2];
;             const int srow = tid >> 3, scp = tid & 7;
;             const bf16_t* knp = KN + (tok0 + srow) * 1024 + h * 128 + scp * 8;
;             const bf16_t* krp = KR + (tok0 + srow) * 64 + scp * 8;
;             const bf16_t* vtp = VT + ((tok0 >> 6) * 1024 + h * 128 + srow) * 64 + scp * 8;
;             const int kdst = srow * AT_KP + scp * 16, vdst = AT_VOFF + srow * AT_VP + scp * 16;
.LBB0_1442:
	s_cmp_lt_i32 s58, 4
	s_cselect_b64 s[0:1], -1, 0
	s_and_b64 s[4:5], s[0:1], s[4:5]
	s_andn2_b64 vcc, exec, s[4:5]
	s_cbranch_vccnz .LBB0_1460
	v_mov_b32_e32 v1, v192
	s_cmpk_gt_i32 s73, 0x3ff
	s_nop 0
	v_readfirstlane_b32 s0, v1
	s_cbranch_scc1 .LBB0_1460
	v_and_b32_e32 v166, 31, v1
	v_bfe_u32 v3, v1, 5, 1
	v_mov_b32_e32 v0, 0
	v_ashrrev_i32_e32 v174, 3, v1
	v_and_b32_e32 v1, 7, v1
	v_readlane_b32 s6, v255, 10
	v_lshlrev_b32_e32 v176, 4, v1
	v_mov_b32_e32 v177, v0
	v_readlane_b32 s7, v255, 11
	s_movk_i32 s1, 0x190
	v_lshlrev_b32_e32 v168, 3, v3
	v_lshl_add_u64 v[178:179], s[6:7], 0, v[176:177]
	v_mad_u64_u32 v[182:183], s[6:7], v174, s1, v[176:177]
	v_lshlrev_b32_e32 v170, 4, v3
	v_lshlrev_b32_e32 v183, 2, v3
	v_mbcnt_lo_u32_b32 v3, -1, 0
	v_mbcnt_hi_u32_b32 v3, -1, v3
	s_waitcnt lgkmcnt(0)
	v_and_b32_e32 v5, 64, v3
	s_movk_i32 s1, 0xfef8
	v_xor_b32_e32 v4, 32, v3
	v_add_u32_e32 v5, 64, v5
	v_ashrrev_i32_e32 v175, 31, v174
	v_lshlrev_b32_e32 v2, 3, v1
	v_mul_lo_u32 v1, v174, s1
	v_cmp_lt_i32_e32 vcc, v4, v5
	s_movk_i32 s1, 0x88
	v_mad_u64_u32 v[186:187], s[8:9], v174, s1, v[176:177]
	v_cndmask_b32_e32 v3, v3, v4, vcc
	v_lshlrev_b64 v[4:5], 7, v[174:175]
	v_add_u32_e32 v167, 0, v182
	v_lshl_add_u64 v[4:5], s[54:55], 0, v[4:5]
	s_mov_b64 s[8:9], 0x8002000
	s_ashr_i32 s0, s0, 1
	v_mov_b32_e32 v169, v0
	v_mov_b32_e32 v171, v0
	v_lshl_add_u64 v[188:189], v[4:5], 0, s[8:9]
	v_lshlrev_b64 v[4:5], 11, v[174:175]
	v_add_u32_e32 v1, v167, v1
	s_andn2_b32 s0, s0, 31
	v_lshl_add_u64 v[172:173], s[18:19], 0, v[170:171]
	v_lshl_add_u64 v[180:181], s[48:49], 0, v[176:177]
	s_mov_b32 s7, 0
	v_mul_u32_u24_e32 v171, 0x190, v166
	v_lshlrev_b32_e32 v193, 2, v3
	v_lshl_add_u64 v[184:185], s[54:55], 0, v[168:169]
	v_mul_u32_u24_e32 v169, 0x90, v166
	v_lshl_add_u64 v[190:191], s[56:57], 0, v[4:5]
	v_lshlrev_b32_e32 v196, 1, v2
	v_mov_b32_e32 v197, v0
	s_mov_b64 s[8:9], 0x2000
	s_movk_i32 s1, 0xc00
	s_mov_b32 s20, 0x41000000
	s_mov_b64 s[10:11], 0x20000
	v_add_u32_e32 v187, 0x6400, v1
	v_add_u32_e32 v195, 0x8600, v1
	v_mov_b32_e32 v226, 0xf149f2ca
	s_mov_b32 s21, s73
	s_branch .LBB0_1446

; #define AT_LOAD(t) do { const bf16_t* kn_ = knp + (size_t)(t) * 65536; kreg[0] = *(const u32x4*)(kn_); kreg[1] = *(const u32x4*)(kn_ + 64); kreg[2] = *(const u32x4*)(krp + (size_t)(t) * 4096); \
;                         const bf16_t* vt_ = vtp + (size_t)(t) * 65536; vreg[0] = *(const u32x4*)(vt_); vreg[1] = *(const u32x4*)(vt_ + 4096); } while (0)
; #define AT_STORE(buf) do { ldsp base_ = lds + (buf) * AT_BUF; *(LAS u32x4*)(base_ + kdst) = kreg[0]; *(LAS u32x4*)(base_ + kdst + 128) = kreg[1]; *(LAS u32x4*)(base_ + kdst + 256) = kreg[2]; \
;                            lds_w8x2(base_ + vdst, vreg[0]); lds_w8x2(base_ + vdst + 64 * AT_VP, vreg[1]); } while (0)
; DI void attn_phase(ldsp lds, const bf16_t* Q, const bf16_t* KN, const bf16_t* KR, const bf16_t* VT, bf16_t* O, int vcu, int G) {
;     ...
;             const bf16_t* knp = KN + (tok0 + srow) * 1024 + h * 128 + scp * 8;
;             const bf16_t* krp = KR + (tok0 + srow) * 64 + scp * 8;
;             const bf16_t* vtp = VT + ((tok0 >> 6) * 1024 + h * 128 + srow) * 64 + scp * 8;
;             const int kdst = srow * AT_KP + scp * 16, vdst = AT_VOFF + srow * AT_VP + scp * 16;
;     ...
;             AT_LOAD(0); AT_STORE(0); __syncthreads();
.Lkd_p_skip:
	v_add_co_u32_e32 v106, vcc, v106, v134
	s_nop 1
	v_addc_co_u32_e32 v107, vcc, 0, v107, vcc
	v_add_co_u32_e32 v108, vcc, v108, v135
	s_nop 1
	v_addc_co_u32_e32 v109, vcc, 0, v109, vcc
	v_add_co_u32_e32 v118, vcc, v118, v136
	s_nop 1
	v_addc_co_u32_e32 v119, vcc, 0, v119, vcc
	v_add_co_u32_e32 v120, vcc, v120, v137
	s_nop 1
	v_addc_co_u32_e32 v121, vcc, 0, v121, vcc
	v_lshlrev_b32_e32 v66, 7, v174
	v_add_u32_e32 v66, v66, v176
	v_sub_co_u32_e32 v68, vcc, v206, v66
	s_nop 1
	v_subbrev_co_u32_e32 v69, vcc, 0, v207, vcc
	s_mov_b32 s99, 0x1c71c71d
	v_add_u32_e32 v72, 0, v1
	v_mul_hi_u32 v73, v72, s99
	v_mul_u32_u24_e32 v74, 9, v73
	v_sub_u32_e32 v74, v72, v74
	v_cmp_eq_u32_e32 vcc, 8, v74
	s_nop 1
	v_cndmask_b32_e64 v74, v74, 0, vcc
	v_lshlrev_b32_e32 v75, 7, v73
	v_lshl_add_u32 v75, v74, 4, v75
	v_add_co_u32_e32 v158, vcc, v68, v75
	s_nop 1
	v_addc_co_u32_e32 v159, vcc, 0, v69, vcc
	v_add_u32_e32 v72, 512, v1
	v_mul_hi_u32 v73, v72, s99
	v_mul_u32_u24_e32 v74, 9, v73
	v_sub_u32_e32 v74, v72, v74
	v_cmp_eq_u32_e32 vcc, 8, v74
	s_nop 1
	v_cndmask_b32_e64 v74, v74, 0, vcc
	v_lshlrev_b32_e32 v75, 7, v73
	v_lshl_add_u32 v75, v74, 4, v75
	v_add_co_u32_e32 v160, vcc, v68, v75
	s_nop 1
	v_addc_co_u32_e32 v161, vcc, 0, v69, vcc
	v_add_u32_e32 v72, 1024, v1
	v_mul_hi_u32 v73, v72, s99
	v_mul_u32_u24_e32 v74, 9, v73
	v_sub_u32_e32 v74, v72, v74
	v_cmp_eq_u32_e32 vcc, 8, v74
	s_nop 1
	v_cndmask_b32_e64 v74, v74, 0, vcc
	v_lshlrev_b32_e32 v75, 7, v73
	v_lshl_add_u32 v75, v74, 4, v75
	v_add_co_u32_e32 v162, vcc, v68, v75
	s_nop 1
	v_addc_co_u32_e32 v163, vcc, 0, v69, vcc
	s_lshl_b32 s99, s0, 5
	s_add_i32 s99, s99, 0x6400
	s_mov_b32 m0, s99
	s_nop 0
	global_load_lds_dwordx4 v[158:159], off
	s_add_i32 m0, s99, 0x2000
	s_nop 0
	global_load_lds_dwordx4 v[160:161], off
	s_cmpk_ge_u32 s0, 0x40
	s_cbranch_scc1 .Lvd_p_skip
	s_add_i32 m0, s99, 0x4000
	s_nop 0
	global_load_lds_dwordx4 v[162:163], off
.Lvd_p_skip:
	v_lshl_add_u64 v[158:159], v[158:159], 0, s[10:11]
	v_lshl_add_u64 v[160:161], v[160:161], 0, s[10:11]
	v_lshl_add_u64 v[162:163], v[162:163], 0, s[10:11]
	global_load_dwordx4 v[98:101], v[2:3], off
	global_load_dwordx4 v[102:105], v[2:3], off offset:32
	global_load_dwordx4 v[110:113], v[2:3], off offset:64
	global_load_dwordx4 v[114:117], v[2:3], off offset:96
	global_load_dwordx4 v[122:125], v[2:3], off offset:128
	global_load_dwordx4 v[126:129], v[2:3], off offset:160
	global_load_dwordx4 v[130:133], v[2:3], off offset:192
	global_load_dwordx4 v[138:141], v[2:3], off offset:224
	global_load_dwordx4 v[142:145], v[2:3], off offset:256
	global_load_dwordx4 v[146:149], v[2:3], off offset:288
	global_load_dwordx4 v[150:153], v[2:3], off offset:320
	global_load_dwordx4 v[154:157], v[2:3], off offset:352
	v_mov_b32_e32 v14, v0
	v_mov_b32_e32 v15, v0
	v_mov_b32_e32 v1, v0
	v_mov_b32_e32 v2, v0
	v_mov_b32_e32 v3, v0
	v_mov_b32_e32 v4, v0
	v_mov_b32_e32 v5, v0
	v_mov_b32_e32 v6, v0
	v_mov_b32_e32 v7, v0
	v_mov_b32_e32 v8, v0
	v_mov_b32_e32 v9, v0
	v_mov_b32_e32 v10, v0
	v_mov_b32_e32 v11, v0
	v_mov_b32_e32 v12, v0
	v_mov_b32_e32 v13, v0
	v_mov_b64_e32 v[64:65], v[14:15]
	v_mov_b64_e32 v[48:49], v[14:15]
	v_mov_b64_e32 v[32:33], v[14:15]
	s_lshl_b32 s15, s24, 2
	v_mov_b64_e32 v[62:63], v[12:13]
	v_mov_b64_e32 v[60:61], v[10:11]
	v_mov_b64_e32 v[58:59], v[8:9]
	v_mov_b64_e32 v[56:57], v[6:7]
	v_mov_b64_e32 v[54:55], v[4:5]
	v_mov_b64_e32 v[52:53], v[2:3]
	v_mov_b64_e32 v[50:51], v[0:1]
	v_mov_b64_e32 v[46:47], v[12:13]
	v_mov_b64_e32 v[44:45], v[10:11]
	v_mov_b64_e32 v[42:43], v[8:9]
	v_mov_b64_e32 v[40:41], v[6:7]
	v_mov_b64_e32 v[38:39], v[4:5]
	v_mov_b64_e32 v[36:37], v[2:3]
	v_mov_b64_e32 v[34:35], v[0:1]
	v_mov_b64_e32 v[30:31], v[12:13]
	v_mov_b64_e32 v[28:29], v[10:11]
	v_mov_b64_e32 v[26:27], v[8:9]
	v_mov_b64_e32 v[24:25], v[6:7]
	v_mov_b64_e32 v[22:23], v[4:5]
	v_mov_b64_e32 v[20:21], v[2:3]
	v_mov_b64_e32 v[18:19], v[0:1]
	v_mov_b64_e32 v[16:17], v[14:15]
	s_mov_b32 s6, 0
	v_mov_b32_e32 v229, 0xf149f2ca
	s_add_i32 s15, s15, 4
	s_add_i32 s24, s25, 0x100
	s_or_b32 s25, s14, 31
	v_or_b32_e32 v228, s14, v166
	v_mov_b32_e32 v227, 0
	s_mov_b32 s26, 1
	v_mov_b64_e32 v[220:221], v[216:217]
	v_mov_b64_e32 v[222:223], v[214:215]
	v_mov_b64_e32 v[224:225], v[212:213]
	v_mov_b64_e32 v[14:15], v[12:13]
	v_mov_b64_e32 v[12:13], v[10:11]
	v_mov_b64_e32 v[10:11], v[8:9]
	v_mov_b64_e32 v[8:9], v[6:7]
	v_mov_b64_e32 v[6:7], v[4:5]
	v_mov_b64_e32 v[4:5], v[2:3]
	v_mov_b64_e32 v[2:3], v[0:1]
	s_waitcnt vmcnt(0)
	s_waitcnt lgkmcnt(0)
	s_barrier
	s_branch .LBB0_1450

; #define AT_LOAD(t) do { const bf16_t* kn_ = knp + (size_t)(t) * 65536; kreg[0] = *(const u32x4*)(kn_); kreg[1] = *(const u32x4*)(kn_ + 64); kreg[2] = *(const u32x4*)(krp + (size_t)(t) * 4096); \
;                         const bf16_t* vt_ = vtp + (size_t)(t) * 65536; vreg[0] = *(const u32x4*)(vt_); vreg[1] = *(const u32x4*)(vt_ + 4096); } while (0)
; #define AT_STORE(buf) do { ldsp base_ = lds + (buf) * AT_BUF; *(LAS u32x4*)(base_ + kdst) = kreg[0]; *(LAS u32x4*)(base_ + kdst + 128) = kreg[1]; *(LAS u32x4*)(base_ + kdst + 256) = kreg[2]; \
;                            lds_w8x2(base_ + vdst, vreg[0]); lds_w8x2(base_ + vdst + 64 * AT_VP, vreg[1]); } while (0)
; DI void attn_phase(ldsp lds, const bf16_t* Q, const bf16_t* KN, const bf16_t* KR, const bf16_t* VT, bf16_t* O, int vcu, int G) {
;     ...
;                 if (t + 1 < ntiles) AT_LOAD(t + 1);
;     ...
;                 if (t + 1 < ntiles) AT_STORE(buf ^ 1);
.LBB0_1453:
	s_and_b32 s99, s26, 1
	s_mul_i32 s99, s99, 0xac00
	s_lshl_b32 s98, s0, 5
	s_add_i32 s99, s99, s98
	s_mov_b32 m0, s99
	s_nop 0
	global_load_lds_dwordx4 v[106:107], off
	s_add_i32 m0, s99, 0x2000
	s_nop 0
	global_load_lds_dwordx4 v[108:109], off
	s_add_i32 m0, s99, 0x4000
	s_nop 0
	global_load_lds_dwordx4 v[118:119], off
	s_cmp_lg_u32 s0, 0
	s_cbranch_scc1 .Lkd_l_skip
	s_add_i32 m0, s99, 0x6000
	s_nop 0
	global_load_lds_dwordx4 v[120:121], off
.Lkd_l_skip:
	v_add_co_u32_e32 v106, vcc, v106, v134
	s_nop 1
	v_addc_co_u32_e32 v107, vcc, 0, v107, vcc
	v_add_co_u32_e32 v108, vcc, v108, v135
	s_nop 1
	v_addc_co_u32_e32 v109, vcc, 0, v109, vcc
	v_add_co_u32_e32 v118, vcc, v118, v136
	s_nop 1
	v_addc_co_u32_e32 v119, vcc, 0, v119, vcc
	v_add_co_u32_e32 v120, vcc, v120, v137
	s_nop 1
	v_addc_co_u32_e32 v121, vcc, 0, v121, vcc
	s_add_i32 s99, s99, 0x6400
	s_mov_b32 m0, s99
	s_nop 0
	global_load_lds_dwordx4 v[158:159], off
	s_add_i32 m0, s99, 0x2000
	s_nop 0
	global_load_lds_dwordx4 v[160:161], off
	s_cmpk_ge_u32 s0, 0x40
	s_cbranch_scc1 .Lvd_l_skip
	s_add_i32 m0, s99, 0x4000
	s_nop 0
	global_load_lds_dwordx4 v[162:163], off
.Lvd_l_skip:
	v_lshl_add_u64 v[158:159], v[158:159], 0, s[10:11]
	v_lshl_add_u64 v[160:161], v[160:161], 0, s[10:11]
	v_lshl_add_u64 v[162:163], v[162:163], 0, s[10:11]
	s_add_i32 s27, s26, -1
	s_and_b32 s27, s27, 1
	s_cmp_gt_i32 s6, s25
	s_cbranch_scc1 .LBB0_1452
; #define LAS __attribute__((address_space(3)))
; DI int crow(int reg, int hh) { return (reg & 3) + 8 * (reg >> 2) + 4 * hh; }
; #define MFMA32(a, b, c) __builtin_amdgcn_mfma_f32_32x32x16_bf16((a), (b), (c), 0, 0, 0)
; DI void attn_phase(ldsp lds, const bf16_t* Q, const bf16_t* KN, const bf16_t* KR, const bf16_t* VT, bf16_t* O, int vcu, int G) {
;     ...
;                 const int buf = t & 1, key0 = t * 64;
;                 if (t + 1 < ntiles) AT_LOAD(t + 1);
;                 if (key0 <= q0 + 31) {
;                     ldsp Lb = lds + buf * AT_BUF;
;                     f32x16 s0, s1;
; #pragma unroll
;                     for (int r = 0; r < 16; ++r) { s0[r] = 0.f; s1[r] = 0.f; }
;                     ldsp kb = Lb + l31 * AT_KP + hh * 16;
;                     bf16x8 kf[6];
; #pragma unroll
;                     for (int i = 0; i < 6; ++i) kf[i] = *(const LAS bf16x8*)(kb + (i & 1) * 32 * AT_KP + (i >> 1) * 32);
; #pragma unroll
;                     for (int i = 0; i < 24; ++i) { const bf16x8 cur = kf[i % 6];
;                         if (i + 6 < 24) kf[i % 6] = *(const LAS bf16x8*)(kb + ((i + 6) & 1) * 32 * AT_KP + ((i + 6) >> 1) * 32);
;                         if (i & 1) s1 = MFMA32(cur, qf[i >> 1], s1); else s0 = MFMA32(cur, qf[i >> 1], s0); }
; #pragma unroll
;                     for (int i = 0; i < 6; ++i) __builtin_amdgcn_sched_group_barrier(0x100, 1, 0);
; #pragma unroll
;                     for (int i = 0; i < 18; ++i) { __builtin_amdgcn_sched_group_barrier(0x008, 1, 0); __builtin_amdgcn_sched_group_barrier(0x100, 1, 0); }
; #pragma unroll
;                     for (int i = 0; i < 6; ++i) __builtin_amdgcn_sched_group_barrier(0x008, 1, 0);
;                     if (key0 + 63 > q0) {
;                         const int qpos = q0 + l31;
; #pragma unroll
;                         for (int r = 0; r < 16; ++r) { const int key = key0 + crow(r, hh); if (key > qpos) s0[r] = -1e30f; if (key + 32 > qpos) s1[r] = -1e30f; }
;     ...
;                                 const bf16x8 va = lds_8x2(Lb + AT_VOFF + (d * 32 + l31) * AT_VP + (kb2 * 32 + 16 * s2 + 4 * hh) * 2, 16);
.LBB0_1454:
	s_mul_i32 s28, s27, 0xac00
	s_add_i32 s28, s28, 0
	v_add3_u32 v1, s28, v171, v170
	ds_read_b128 v[66:69], v1 offset:12800
	ds_read_b128 v[70:73], v1
	ds_read_b128 v[230:233], v1 offset:32
	ds_read_b128 v[234:237], v1 offset:12832
	ds_read_b128 v[238:241], v1 offset:64
	ds_read_b128 v[242:245], v1 offset:12864
	s_add_i32 s29, s6, 63
	s_cmp_le_i32 s29, s14
	s_waitcnt lgkmcnt(4)
	v_mfma_f32_32x32x16_bf16 v[82:97], v[70:73], v[98:101], 0
	ds_read_b128 v[246:249], v1 offset:96
	v_mfma_f32_32x32x16_bf16 v[66:81], v[66:69], v[98:101], 0
	ds_read_b128 v[250:253], v1 offset:12896
	s_waitcnt lgkmcnt(5)
	v_mfma_f32_32x32x16_bf16 v[82:97], v[230:233], v[102:105], v[82:97]
	ds_read_b128 v[230:233], v1 offset:128
	s_waitcnt lgkmcnt(5)
	v_mfma_f32_32x32x16_bf16 v[66:81], v[234:237], v[102:105], v[66:81]
	ds_read_b128 v[234:237], v1 offset:12928
	s_waitcnt lgkmcnt(5)
	v_mfma_f32_32x32x16_bf16 v[82:97], v[238:241], v[110:113], v[82:97]
	ds_read_b128 v[238:241], v1 offset:160
	s_waitcnt lgkmcnt(5)
	v_mfma_f32_32x32x16_bf16 v[66:81], v[242:245], v[110:113], v[66:81]
	ds_read_b128 v[242:245], v1 offset:12960
	s_waitcnt lgkmcnt(5)
	v_mfma_f32_32x32x16_bf16 v[82:97], v[246:249], v[114:117], v[82:97]
	ds_read_b128 v[246:249], v1 offset:192
	s_waitcnt lgkmcnt(5)
	v_mfma_f32_32x32x16_bf16 v[66:81], v[250:253], v[114:117], v[66:81]
	ds_read_b128 v[250:253], v1 offset:12992
	s_waitcnt lgkmcnt(5)
	v_mfma_f32_32x32x16_bf16 v[82:97], v[230:233], v[122:125], v[82:97]
	ds_read_b128 v[230:233], v1 offset:224
	s_waitcnt lgkmcnt(5)
	v_mfma_f32_32x32x16_bf16 v[66:81], v[234:237], v[122:125], v[66:81]
	ds_read_b128 v[234:237], v1 offset:13024
	s_waitcnt lgkmcnt(5)
	v_mfma_f32_32x32x16_bf16 v[82:97], v[238:241], v[126:129], v[82:97]
	ds_read_b128 v[238:241], v1 offset:256
	s_waitcnt lgkmcnt(5)
	v_mfma_f32_32x32x16_bf16 v[66:81], v[242:245], v[126:129], v[66:81]
	ds_read_b128 v[242:245], v1 offset:13056
	s_waitcnt lgkmcnt(5)
	v_mfma_f32_32x32x16_bf16 v[82:97], v[246:249], v[130:133], v[82:97]
	ds_read_b128 v[246:249], v1 offset:288
	s_waitcnt lgkmcnt(5)
	v_mfma_f32_32x32x16_bf16 v[66:81], v[250:253], v[130:133], v[66:81]
	ds_read_b128 v[250:253], v1 offset:13088
	s_waitcnt lgkmcnt(5)
	v_mfma_f32_32x32x16_bf16 v[82:97], v[230:233], v[138:141], v[82:97]
	ds_read_b128 v[230:233], v1 offset:320
	s_waitcnt lgkmcnt(5)
	v_mfma_f32_32x32x16_bf16 v[66:81], v[234:237], v[138:141], v[66:81]
	ds_read_b128 v[234:237], v1 offset:13120
	s_waitcnt lgkmcnt(5)
	v_mfma_f32_32x32x16_bf16 v[82:97], v[238:241], v[142:145], v[82:97]
	ds_read_b128 v[238:241], v1 offset:352
	s_waitcnt lgkmcnt(5)
	v_mfma_f32_32x32x16_bf16 v[66:81], v[242:245], v[142:145], v[66:81]
	ds_read_b128 v[242:245], v1 offset:13152
	s_waitcnt lgkmcnt(5)
	v_mfma_f32_32x32x16_bf16 v[82:97], v[246:249], v[146:149], v[82:97]
	s_waitcnt lgkmcnt(4)
	v_mfma_f32_32x32x16_bf16 v[66:81], v[250:253], v[146:149], v[66:81]
	s_waitcnt lgkmcnt(3)
	v_mfma_f32_32x32x16_bf16 v[82:97], v[230:233], v[150:153], v[82:97]
	s_waitcnt lgkmcnt(2)
	v_mfma_f32_32x32x16_bf16 v[66:81], v[234:237], v[150:153], v[66:81]
	s_waitcnt lgkmcnt(1)
	v_mfma_f32_32x32x16_bf16 v[82:97], v[238:241], v[154:157], v[82:97]
	s_waitcnt lgkmcnt(0)
	v_mfma_f32_32x32x16_bf16 v[66:81], v[242:245], v[154:157], v[66:81]
	v_add3_u32 v253, s28, v170, v169
	ds_read_b128 v[232:235], v253 offset:25600
	ds_read_b128 v[236:239], v253 offset:30208
	ds_read_b128 v[240:243], v253 offset:34816
	ds_read_b128 v[244:247], v253 offset:39424
	ds_read_b128 v[248:251], v253 offset:25632
	s_cbranch_scc1 .LBB0_1456
	v_add_u32_e32 v1, s6, v183
	v_add_u32_e32 v230, 32, v1
	v_cmp_le_i32_e32 vcc, v230, v228
	v_add_u32_e32 v230, 33, v1
	s_nop 6
	v_cndmask_b32_e32 v66, v226, v66, vcc
	v_cmp_lt_i32_e32 vcc, v1, v228
	s_nop 1
	v_cndmask_b32_e32 v83, v226, v83, vcc
	v_cmp_le_i32_e32 vcc, v1, v228
	s_nop 1
	v_cndmask_b32_e32 v82, v226, v82, vcc
	v_cmp_le_i32_e32 vcc, v230, v228
	v_add_u32_e32 v230, 2, v1
	s_nop 0
	v_cndmask_b32_e32 v67, v226, v67, vcc
	v_cmp_le_i32_e32 vcc, v230, v228
	v_add_u32_e32 v230, 34, v1
	s_nop 0
	v_cndmask_b32_e32 v84, v226, v84, vcc
	v_cmp_le_i32_e32 vcc, v230, v228
	v_add_u32_e32 v230, 3, v1
	s_nop 0
	v_cndmask_b32_e32 v68, v226, v68, vcc
	v_cmp_le_i32_e32 vcc, v230, v228
	v_add_u32_e32 v230, 35, v1
	s_nop 0
	v_cndmask_b32_e32 v85, v226, v85, vcc
	v_cmp_le_i32_e32 vcc, v230, v228
	v_add_u32_e32 v230, 8, v1
	s_nop 0
	v_cndmask_b32_e32 v69, v226, v69, vcc
	v_cmp_le_i32_e32 vcc, v230, v228
	v_add_u32_e32 v230, 40, v1
	s_nop 0
	v_cndmask_b32_e32 v86, v226, v86, vcc
	v_cmp_le_i32_e32 vcc, v230, v228
	v_add_u32_e32 v230, 9, v1
	s_nop 0
	v_cndmask_b32_e32 v70, v226, v70, vcc
	v_cmp_le_i32_e32 vcc, v230, v228
	v_add_u32_e32 v230, 41, v1
	s_nop 0
	v_cndmask_b32_e32 v87, v226, v87, vcc
	v_cmp_le_i32_e32 vcc, v230, v228
	v_add_u32_e32 v230, 10, v1
	s_nop 0
	v_cndmask_b32_e32 v71, v226, v71, vcc
	v_cmp_le_i32_e32 vcc, v230, v228
	v_add_u32_e32 v230, 42, v1
	s_nop 0
	v_cndmask_b32_e32 v88, v226, v88, vcc
	v_cmp_le_i32_e32 vcc, v230, v228
	v_add_u32_e32 v230, 11, v1
	s_nop 0
	v_cndmask_b32_e32 v72, v226, v72, vcc
	v_cmp_le_i32_e32 vcc, v230, v228
	v_add_u32_e32 v230, 43, v1
	s_nop 0
	v_cndmask_b32_e32 v89, v226, v89, vcc
	v_cmp_le_i32_e32 vcc, v230, v228
	v_add_u32_e32 v230, 16, v1
	s_nop 0
	v_cndmask_b32_e32 v73, v226, v73, vcc
	v_cmp_le_i32_e32 vcc, v230, v228
	v_add_u32_e32 v230, 48, v1
	s_nop 0
	v_cndmask_b32_e32 v90, v226, v90, vcc
	v_cmp_le_i32_e32 vcc, v230, v228
	v_add_u32_e32 v230, 17, v1
	s_nop 0
	v_cndmask_b32_e32 v74, v226, v74, vcc
	v_cmp_le_i32_e32 vcc, v230, v228
	v_add_u32_e32 v230, 49, v1
	s_nop 0
	v_cndmask_b32_e32 v91, v226, v91, vcc
	v_cmp_le_i32_e32 vcc, v230, v228
	v_add_u32_e32 v230, 18, v1
	s_nop 0
	v_cndmask_b32_e32 v75, v226, v75, vcc
	v_cmp_le_i32_e32 vcc, v230, v228
	v_add_u32_e32 v230, 50, v1
	s_nop 0
	v_cndmask_b32_e32 v92, v226, v92, vcc
	v_cmp_le_i32_e32 vcc, v230, v228
	v_add_u32_e32 v230, 19, v1
	s_nop 0
	v_cndmask_b32_e32 v76, v226, v76, vcc
	v_cmp_le_i32_e32 vcc, v230, v228
	v_add_u32_e32 v230, 51, v1
	s_nop 0
	v_cndmask_b32_e32 v93, v226, v93, vcc
	v_cmp_le_i32_e32 vcc, v230, v228
	v_add_u32_e32 v230, 24, v1
	s_nop 0
	v_cndmask_b32_e32 v77, v226, v77, vcc
	v_cmp_le_i32_e32 vcc, v230, v228
	v_add_u32_e32 v230, 56, v1
	s_nop 0
	v_cndmask_b32_e32 v94, v226, v94, vcc
	v_cmp_le_i32_e32 vcc, v230, v228
	v_add_u32_e32 v230, 25, v1
	s_nop 0
	v_cndmask_b32_e32 v78, v226, v78, vcc
	v_cmp_le_i32_e32 vcc, v230, v228
	v_add_u32_e32 v230, 57, v1
	s_nop 0
	v_cndmask_b32_e32 v95, v226, v95, vcc
	v_cmp_le_i32_e32 vcc, v230, v228
	v_add_u32_e32 v230, 26, v1
	s_nop 0
	v_cndmask_b32_e32 v79, v226, v79, vcc
	v_cmp_le_i32_e32 vcc, v230, v228
	v_add_u32_e32 v230, 58, v1
	s_nop 0
	v_cndmask_b32_e32 v96, v226, v96, vcc
	v_cmp_le_i32_e32 vcc, v230, v228
	v_add_u32_e32 v230, 27, v1
	v_add_u32_e32 v1, 59, v1
	v_cndmask_b32_e32 v80, v226, v80, vcc
	v_cmp_le_i32_e32 vcc, v230, v228
	s_nop 1
	v_cndmask_b32_e32 v97, v226, v97, vcc
	v_cmp_le_i32_e32 vcc, v1, v228
	s_nop 1
	v_cndmask_b32_e32 v81, v226, v81, vcc

; #define MFMA32(a, b, c) __builtin_amdgcn_mfma_f32_32x32x16_bf16((a), (b), (c), 0, 0, 0)
; #define AT_STORE(buf) do { ldsp base_ = lds + (buf) * AT_BUF; *(LAS u32x4*)(base_ + kdst) = kreg[0]; *(LAS u32x4*)(base_ + kdst + 128) = kreg[1]; *(LAS u32x4*)(base_ + kdst + 256) = kreg[2]; \
;                            lds_w8x2(base_ + vdst, vreg[0]); lds_w8x2(base_ + vdst + 64 * AT_VP, vreg[1]); } while (0)
; DI void attn_phase(ldsp lds, const bf16_t* Q, const bf16_t* KN, const bf16_t* KR, const bf16_t* VT, bf16_t* O, int vcu, int G) {
;     ...
;                     float rs = 0.f;
; #pragma unroll
;                     for (int r = 0; r < 16; ++r) { s0[r] = __builtin_amdgcn_exp2f(s0[r] - mrun); s1[r] = __builtin_amdgcn_exp2f(s1[r] - mrun); rs += s0[r] + s1[r]; }
;                     lrun += rs;
;                     bf16x8 pa[2][2];
;                     pa[0][0] = pack8(s0, 0); pa[0][1] = pack8(s0, 1); pa[1][0] = pack8(s1, 0); pa[1][1] = pack8(s1, 1);
; #pragma unroll
;                     for (int kb2 = 0; kb2 < 2; ++kb2)
; #pragma unroll
;                         for (int s2 = 0; s2 < 2; ++s2)
; #pragma unroll
;                             for (int d = 0; d < 4; ++d) {
;                                 const bf16x8 va = lds_8x2(Lb + AT_VOFF + (d * 32 + l31) * AT_VP + (kb2 * 32 + 16 * s2 + 4 * hh) * 2, 16);
;                                 o[d] = MFMA32(va, pa[kb2][s2], o[d]); }
;                 }
;                 if (t + 1 < ntiles) AT_STORE(buf ^ 1);
;                 __syncthreads();
.LBB0_1458:
	s_sleep 8
	v_sub_f32_e32 v82, v82, v229
	v_sub_f32_e32 v83, v83, v229
	v_sub_f32_e32 v84, v84, v229
	v_sub_f32_e32 v85, v85, v229
	v_sub_f32_e32 v86, v86, v229
	v_sub_f32_e32 v87, v87, v229
	v_sub_f32_e32 v88, v88, v229
	v_sub_f32_e32 v89, v89, v229
	v_exp_f32_e32 v82, v82
	v_exp_f32_e32 v83, v83
	v_exp_f32_e32 v84, v84
	v_exp_f32_e32 v85, v85
	v_exp_f32_e32 v86, v86
	v_exp_f32_e32 v87, v87
	v_exp_f32_e32 v88, v88
	v_exp_f32_e32 v89, v89
	v_add_f32_e32 v1, v82, v84
	v_add_f32_e32 v230, v83, v85
	v_add_f32_e32 v1, v1, v86
	v_add_f32_e32 v230, v230, v87
	v_add_f32_e32 v1, v1, v88
	v_add_f32_e32 v230, v230, v89
	v_cvt_pk_bf16_f32 v82, v82, v83
	v_cvt_pk_bf16_f32 v83, v84, v85
	v_cvt_pk_bf16_f32 v84, v86, v87
	v_cvt_pk_bf16_f32 v85, v88, v89
	s_nop 1
	v_permlane32_swap_b32_e32 v82, v84
	v_permlane32_swap_b32_e32 v83, v85
	s_nop 1
	s_waitcnt lgkmcnt(4)
	v_mfma_f32_32x32x16_bf16 v[50:65], v[232:235], v[82:85], v[50:65]
	ds_read_b128 v[232:235], v253 offset:30240
	v_sub_f32_e32 v90, v90, v229
	v_sub_f32_e32 v91, v91, v229
	v_sub_f32_e32 v92, v92, v229
	v_sub_f32_e32 v93, v93, v229
	v_sub_f32_e32 v94, v94, v229
	v_sub_f32_e32 v95, v95, v229
	v_sub_f32_e32 v96, v96, v229
	v_sub_f32_e32 v97, v97, v229
	s_waitcnt lgkmcnt(4)
	v_mfma_f32_32x32x16_bf16 v[34:49], v[236:239], v[82:85], v[34:49]
	ds_read_b128 v[236:239], v253 offset:34848
	v_exp_f32_e32 v90, v90
	v_exp_f32_e32 v91, v91
	v_exp_f32_e32 v92, v92
	v_exp_f32_e32 v93, v93
	v_exp_f32_e32 v94, v94
	v_exp_f32_e32 v95, v95
	v_exp_f32_e32 v96, v96
	v_exp_f32_e32 v97, v97
	s_waitcnt lgkmcnt(4)
	v_mfma_f32_32x32x16_bf16 v[18:33], v[240:243], v[82:85], v[18:33]
	ds_read_b128 v[240:243], v253 offset:39456
	v_add_f32_e32 v1, v1, v90
	v_add_f32_e32 v230, v230, v91
	v_add_f32_e32 v1, v1, v92
	v_add_f32_e32 v230, v230, v93
	v_add_f32_e32 v1, v1, v94
	v_add_f32_e32 v230, v230, v95
	v_add_f32_e32 v1, v1, v96
	v_add_f32_e32 v230, v230, v97
	s_waitcnt lgkmcnt(4)
	v_mfma_f32_32x32x16_bf16 v[2:17], v[244:247], v[82:85], v[2:17]
	ds_read_b128 v[244:247], v253 offset:25664
	v_cvt_pk_bf16_f32 v90, v90, v91
	v_cvt_pk_bf16_f32 v91, v92, v93
	v_cvt_pk_bf16_f32 v92, v94, v95
	v_cvt_pk_bf16_f32 v93, v96, v97
	s_nop 1
	v_permlane32_swap_b32_e32 v90, v92
	v_permlane32_swap_b32_e32 v91, v93
	s_nop 1
	s_waitcnt lgkmcnt(4)
	v_mfma_f32_32x32x16_bf16 v[50:65], v[248:251], v[90:93], v[50:65]
	ds_read_b128 v[248:251], v253 offset:30272
	v_sub_f32_e32 v66, v66, v229
	v_sub_f32_e32 v67, v67, v229
	v_sub_f32_e32 v68, v68, v229
	v_sub_f32_e32 v69, v69, v229
	v_sub_f32_e32 v70, v70, v229
	v_sub_f32_e32 v71, v71, v229
	v_sub_f32_e32 v72, v72, v229
	v_sub_f32_e32 v73, v73, v229
	s_waitcnt lgkmcnt(4)
	v_mfma_f32_32x32x16_bf16 v[34:49], v[232:235], v[90:93], v[34:49]
	ds_read_b128 v[232:235], v253 offset:34880
	v_exp_f32_e32 v66, v66
	v_exp_f32_e32 v67, v67
	v_exp_f32_e32 v68, v68
	v_exp_f32_e32 v69, v69
	v_exp_f32_e32 v70, v70
	v_exp_f32_e32 v71, v71
	v_exp_f32_e32 v72, v72
	v_exp_f32_e32 v73, v73
	s_waitcnt lgkmcnt(4)
	v_mfma_f32_32x32x16_bf16 v[18:33], v[236:239], v[90:93], v[18:33]
	ds_read_b128 v[236:239], v253 offset:39488
	v_add_f32_e32 v1, v1, v66
	v_add_f32_e32 v230, v230, v67
	v_add_f32_e32 v1, v1, v68
	v_add_f32_e32 v230, v230, v69
	v_add_f32_e32 v1, v1, v70
	v_add_f32_e32 v230, v230, v71
	v_add_f32_e32 v1, v1, v72
	v_add_f32_e32 v230, v230, v73
	s_waitcnt lgkmcnt(4)
	v_mfma_f32_32x32x16_bf16 v[2:17], v[240:243], v[90:93], v[2:17]
	ds_read_b128 v[240:243], v253 offset:25696
	v_cvt_pk_bf16_f32 v66, v66, v67
	v_cvt_pk_bf16_f32 v67, v68, v69
	v_cvt_pk_bf16_f32 v68, v70, v71
	v_cvt_pk_bf16_f32 v69, v72, v73
	s_nop 1
	v_permlane32_swap_b32_e32 v66, v68
	v_permlane32_swap_b32_e32 v67, v69
	s_nop 1
	s_waitcnt lgkmcnt(4)
	v_mfma_f32_32x32x16_bf16 v[50:65], v[244:247], v[66:69], v[50:65]
	ds_read_b128 v[244:247], v253 offset:30304
	v_sub_f32_e32 v74, v74, v229
	v_sub_f32_e32 v75, v75, v229
	v_sub_f32_e32 v76, v76, v229
	v_sub_f32_e32 v77, v77, v229
	v_sub_f32_e32 v78, v78, v229
	v_sub_f32_e32 v79, v79, v229
	v_sub_f32_e32 v80, v80, v229
	v_sub_f32_e32 v81, v81, v229
	s_waitcnt lgkmcnt(4)
	v_mfma_f32_32x32x16_bf16 v[34:49], v[248:251], v[66:69], v[34:49]
	ds_read_b128 v[248:251], v253 offset:34912
	v_exp_f32_e32 v74, v74
	v_exp_f32_e32 v75, v75
	v_exp_f32_e32 v76, v76
	v_exp_f32_e32 v77, v77
	v_exp_f32_e32 v78, v78
	v_exp_f32_e32 v79, v79
	v_exp_f32_e32 v80, v80
	v_exp_f32_e32 v81, v81
	s_waitcnt lgkmcnt(4)
	v_mfma_f32_32x32x16_bf16 v[18:33], v[232:235], v[66:69], v[18:33]
	ds_read_b128 v[232:235], v253 offset:39520
	v_add_f32_e32 v1, v1, v74
	v_add_f32_e32 v230, v230, v75
	v_add_f32_e32 v1, v1, v76
	v_add_f32_e32 v230, v230, v77
	v_add_f32_e32 v1, v1, v78
	v_add_f32_e32 v230, v230, v79
	v_add_f32_e32 v1, v1, v80
	v_add_f32_e32 v230, v230, v81
	s_waitcnt lgkmcnt(4)
	v_mfma_f32_32x32x16_bf16 v[2:17], v[236:239], v[66:69], v[2:17]
	v_cvt_pk_bf16_f32 v74, v74, v75
	v_cvt_pk_bf16_f32 v75, v76, v77
	v_cvt_pk_bf16_f32 v76, v78, v79
	v_cvt_pk_bf16_f32 v77, v80, v81
	s_nop 1
	v_permlane32_swap_b32_e32 v74, v76
	v_permlane32_swap_b32_e32 v75, v77
	s_nop 1
	s_waitcnt lgkmcnt(3)
	v_mfma_f32_32x32x16_bf16 v[50:65], v[240:243], v[74:77], v[50:65]
	s_waitcnt lgkmcnt(2)
	v_mfma_f32_32x32x16_bf16 v[34:49], v[244:247], v[74:77], v[34:49]
	s_waitcnt lgkmcnt(1)
	v_mfma_f32_32x32x16_bf16 v[18:33], v[248:251], v[74:77], v[18:33]
	s_waitcnt lgkmcnt(0)
	v_mfma_f32_32x32x16_bf16 v[2:17], v[232:235], v[74:77], v[2:17]
	v_add_f32_e32 v1, v1, v230
	v_add_f32_e32 v227, v227, v1
	s_andn2_b64 vcc, exec, s[16:17]
	s_cbranch_vccnz .LBB0_1449
.LBB0_1459:
	s_waitcnt vmcnt(0)
	s_branch .LBB0_1449
